# static priority raise for the younger wave half (waves 4-7) before every 8-wave GEMM loop, per-MFMA-block s_setprio flips deleted
# speedup vs baseline: 1.0007x; 1.0007x over previous
.LBB0_821:
	v_lshrrev_b32_e32 v3, 1, v10
	v_lshrrev_b32_e32 v4, 5, v10
	v_and_b32_e32 v3, 24, v3
	v_and_b32_e32 v4, 4, v4
	v_bfe_u32 v5, v10, 2, 2
	s_ashr_i32 s0, s7, 3
	v_lshlrev_b32_e32 v1, 4, v10
	v_and_b32_e32 v2, 32, v10
	v_bfe_u32 v13, v10, 2, 4
	v_or3_b32 v3, v4, v5, v3
	v_lshrrev_b32_e32 v4, 3, v10
	s_movk_i32 s7, 0x70
	v_bitop3_b32 v11, v1, v2, 48 bitop3:0x6c
	v_and_b32_e32 v12, 64, v10
	v_and_or_b32 v5, v4, s7, v13
	s_movk_i32 s7, 0x60
	v_add_u32_e32 v14, 0x2000, v1
	v_or_b32_e32 v2, v11, v12
	v_and_or_b32 v4, v4, s7, v3
	v_lshrrev_b32_e32 v1, 7, v14
	s_movk_i32 s7, 0xf0
	s_add_i32 s0, s6, s0
	v_lshl_or_b32 v132, v4, 11, v2
	v_and_or_b32 v4, v1, s7, v13
	s_movk_i32 s7, 0xe0
	s_mul_hi_i32 s6, s0, 0x2e8ba2e9
	v_and_or_b32 v1, v1, s7, v3
	s_lshr_b32 s7, s6, 31
	s_ashr_i32 s6, s6, 5
	s_add_i32 s6, s6, s7
	s_lshl_b32 s8, s6, 3
	s_sub_i32 s7, 0x45, s8
	s_mulk_i32 s6, 0xb0
	s_min_u32 s9, s7, 8
	s_sub_i32 s11, s0, s6
	v_lshl_or_b32 v130, v5, 11, v2
	v_lshl_or_b32 v134, v4, 11, v2
	v_lshl_or_b32 v136, v1, 11, v2
	s_sext_i32_i16 s0, s11
	v_cvt_f32_ubyte0_e32 v2, s9
	v_cvt_f32_i32_e32 v1, s0
	v_rcp_iflag_f32_e32 v3, v2
	s_lshr_b32 s10, s12, 6
	s_ashr_i32 s0, s0, 30
	s_lshr_b32 s1, s12, 8
	v_mul_f32_e32 v3, v1, v3
	v_trunc_f32_e32 v3, v3
	v_fma_f32 v1, -v3, v2, v1
	v_cvt_i32_f32_e32 v3, v3
	s_lshl_b32 s33, s10, 10
	s_or_b32 s0, s0, 1
	v_cmp_ge_f32_e64 s[6:7], |v1|, v2
	s_and_b64 s[6:7], s[6:7], exec
	s_cselect_b32 s0, s0, 0
	v_readfirstlane_b32 s6, v3
	s_add_i32 s0, s6, s0
	s_mul_i32 s6, s0, s9
	s_sub_i32 s6, s11, s6
	s_sext_i32_i16 s6, s6
	s_add_i32 s22, s8, s6
	s_ashr_i32 s23, s22, 31
	s_bfe_i64 s[8:9], s[0:1], 0x100000
	s_lshl_b64 s[6:7], s[22:23], 19
	s_lshl_b64 s[8:9], s[8:9], 19
	s_add_u32 s68, s28, s8
	s_addc_u32 s69, s29, s9
	s_add_i32 s23, s33, 0
	s_add_i32 m0, s23, 0x10000
	v_mov_b32_e32 v133, 0
	global_load_lds_dwordx4 v132, s[68:69]
	s_add_i32 m0, s23, 0x12000
	s_add_u32 s8, s68, 0x40000
	global_load_lds_dwordx4 v136, s[68:69]
	s_addc_u32 s9, s69, 0
	s_add_i32 m0, s23, 0x14000
	v_mov_b32_e32 v137, v133
	global_load_lds_dwordx4 v132, s[8:9]
	s_add_i32 m0, s23, 0x16000
	s_add_u32 s66, s88, s6
	s_addc_u32 s67, s89, s7
	s_add_i32 s35, s23, 0x2000
	global_load_lds_dwordx4 v136, s[8:9]
	s_mov_b32 m0, s23
	s_add_u32 s6, s66, 0x40000
	global_load_lds_dwordx4 v130, s[66:67]
	s_mov_b32 m0, s35
	s_addc_u32 s7, s67, 0
	s_add_i32 s52, s23, 0x4000
	global_load_lds_dwordx4 v134, s[66:67]
	s_mov_b32 m0, s52
	s_add_i32 s53, s23, 0x6000
	global_load_lds_dwordx4 v130, s[6:7]
	s_mov_b32 m0, s53
	v_mov_b32_e32 v131, v133
	global_load_lds_dwordx4 v134, s[6:7]
	v_mov_b32_e32 v135, v133
	s_cmp_eq_u32 s1, 1
	s_mov_b32 s54, 0
	v_lshl_add_u64 v[8:9], s[68:69], 0, v[132:133]
	v_lshl_add_u64 v[6:7], s[68:69], 0, v[136:137]
	v_lshl_add_u64 v[2:3], s[66:67], 0, v[130:131]
	s_cselect_b64 s[6:7], -1, 0
	s_cmp_lg_u32 s1, 1
	v_lshl_add_u64 v[4:5], s[66:67], 0, v[134:135]
	s_cbranch_scc1 .LBB0_823
	s_setprio 1
	s_barrier

.LBB0_839:
	s_waitcnt vmcnt(0)
	s_setprio 0
	s_barrier

.LBB0_901:
	s_add_u32 s10, s28, 0xb00000
	v_bfe_u32 v171, v1, 4, 2
	v_cndmask_b32_e64 v2, 0, 1, s[4:5]
	s_addc_u32 s11, s29, 0
	v_lshlrev_b32_e32 v168, 4, v1
	v_and_b32_e32 v169, 15, v1
	v_cmp_ne_u32_e64 s[0:1], 1, v2
	s_andn2_b64 vcc, exec, s[4:5]
	v_lshlrev_b32_e32 v170, 3, v171
	s_cbranch_vccnz .LBB0_1029
	v_lshrrev_b32_e32 v4, 1, v1
	v_lshrrev_b32_e32 v5, 5, v1
	v_and_b32_e32 v4, 24, v4
	v_and_b32_e32 v5, 4, v5
	v_bfe_u32 v6, v1, 2, 2
	v_and_b32_e32 v2, 32, v1
	v_bfe_u32 v3, v1, 2, 4
	v_or3_b32 v4, v5, v6, v4
	v_lshrrev_b32_e32 v5, 3, v1
	s_movk_i32 s3, 0x70
	v_bitop3_b32 v10, v168, v2, 48 bitop3:0x6c
	v_and_b32_e32 v11, 64, v1
	v_and_or_b32 v6, v5, s3, v3
	s_movk_i32 s3, 0x60
	v_or_b32_e32 v2, v10, v11
	v_and_or_b32 v5, v5, s3, v4
	v_lshrrev_b32_e32 v2, 1, v2
	v_mul_u32_u24_e32 v5, 0xb00, v5
	v_or_b32_e32 v5, v5, v2
	v_lshlrev_b32_e32 v142, 1, v5
	v_add_u32_e32 v5, 0x2000, v168
	v_lshrrev_b32_e32 v5, 7, v5
	s_movk_i32 s3, 0xf0
	s_lshr_b32 s4, s6, 6
	v_and_or_b32 v3, v5, s3, v3
	s_movk_i32 s3, 0xe0
	v_and_or_b32 v4, v5, s3, v4
	s_lshr_b32 s5, s6, 8
	s_lshl_b32 s3, s4, 10
	s_mul_i32 s9, s14, 0x160000
	v_mul_u32_u24_e32 v13, 0xb00, v3
	s_mul_hi_i32 s8, s14, 0x160000
	s_add_u32 s70, s10, s9
	v_or_b32_e32 v3, v13, v2
	s_addc_u32 s71, s11, s8
	s_add_i32 s33, s3, 0
	v_mul_u32_u24_e32 v12, 0xb00, v6
	v_lshlrev_b32_e32 v144, 1, v3
	v_mul_u32_u24_e32 v3, 0xb00, v4
	s_add_i32 m0, s33, 0x10000
	v_or_b32_e32 v6, v2, v12
	v_or_b32_e32 v2, v3, v2
	global_load_lds_dwordx4 v142, s[70:71]
	s_add_i32 m0, s33, 0x12000
	v_lshlrev_b32_e32 v146, 1, v2
	s_add_u32 s8, s70, 0xb0000
	global_load_lds_dwordx4 v146, s[70:71]
	s_addc_u32 s9, s71, 0
	s_add_i32 m0, s33, 0x14000
	s_mul_i32 s15, s52, 0x160000
	global_load_lds_dwordx4 v142, s[8:9]
	s_add_i32 m0, s33, 0x16000
	s_mul_hi_i32 s7, s52, 0x160000
	s_add_u32 s90, s64, s15
	s_addc_u32 s91, s65, s7
	s_add_i32 s35, s33, 0x2000
	v_lshlrev_b32_e32 v140, 1, v6
	global_load_lds_dwordx4 v146, s[8:9]
	s_mov_b32 m0, s33
	s_add_u32 s8, s90, 0xb0000
	global_load_lds_dwordx4 v140, s[90:91]
	s_mov_b32 m0, s35
	s_addc_u32 s9, s91, 0
	s_add_i32 s54, s33, 0x4000
	global_load_lds_dwordx4 v144, s[90:91]
	s_mov_b32 m0, s54
	s_add_i32 s55, s33, 0x6000
	global_load_lds_dwordx4 v140, s[8:9]
	s_mov_b32 m0, s55
	v_mov_b32_e32 v149, 0
	global_load_lds_dwordx4 v144, s[8:9]
	v_mov_b32_e32 v143, v149
	v_mov_b32_e32 v147, v149
	v_mov_b32_e32 v141, v149
	v_mov_b32_e32 v145, v149
	s_cmp_eq_u32 s5, 1
	s_mov_b32 s15, 0
	v_lshl_add_u64 v[8:9], s[70:71], 0, v[142:143]
	v_lshl_add_u64 v[6:7], s[70:71], 0, v[146:147]
	v_lshl_add_u64 v[2:3], s[90:91], 0, v[140:141]
	s_cselect_b64 s[16:17], -1, 0
	s_cmp_lg_u32 s5, 1
	v_lshl_add_u64 v[4:5], s[90:91], 0, v[144:145]
	s_cbranch_scc1 .LBB0_904
	s_setprio 1
	s_barrier

.LBB0_1146:
	s_andn2_b64 vcc, exec, s[0:1]
	s_cbranch_vccnz .LBB0_1322
	s_waitcnt lgkmcnt(0)
	v_lshrrev_b32_e32 v3, 1, v10
	v_lshrrev_b32_e32 v4, 5, v10
	v_and_b32_e32 v3, 24, v3
	v_and_b32_e32 v4, 4, v4
	v_bfe_u32 v5, v10, 2, 2
	v_lshlrev_b32_e32 v1, 4, v10
	v_and_b32_e32 v2, 32, v10
	v_bfe_u32 v13, v10, 2, 4
	v_or3_b32 v3, v4, v5, v3
	v_lshrrev_b32_e32 v4, 3, v10
	s_movk_i32 s1, 0x70
	v_bitop3_b32 v11, v1, v2, 48 bitop3:0x6c
	v_and_b32_e32 v12, 64, v10
	v_and_or_b32 v5, v4, s1, v13
	s_movk_i32 s1, 0x60
	v_add_u32_e32 v14, 0x2000, v1
	s_add_u32 s3, s28, 0x1080000
	v_or_b32_e32 v2, v11, v12
	v_and_or_b32 v4, v4, s1, v3
	v_lshrrev_b32_e32 v1, 7, v14
	s_movk_i32 s1, 0xf0
	s_addc_u32 s33, s29, 0
	s_lshr_b32 s0, s6, 6
	v_lshl_or_b32 v148, v4, 11, v2
	v_and_or_b32 v4, v1, s1, v13
	s_movk_i32 s1, 0xe0
	s_ashr_i32 s95, s94, 31
	s_ashr_i32 s93, s92, 31
	v_and_or_b32 v1, v1, s1, v3
	s_lshr_b32 s1, s6, 8
	s_lshl_b32 s35, s0, 10
	s_lshl_b64 s[4:5], s[94:95], 19
	s_lshl_b64 s[8:9], s[92:93], 19
	s_add_u32 s96, s3, s8
	s_addc_u32 s97, s33, s9
	s_add_i32 s55, s35, 0
	s_add_i32 m0, s55, 0x10000
	v_lshl_or_b32 v152, v1, 11, v2
	global_load_lds_dwordx4 v148, s[96:97]
	s_add_i32 m0, s55, 0x12000
	s_add_u32 s8, s96, 0x40000
	global_load_lds_dwordx4 v152, s[96:97]
	s_addc_u32 s9, s97, 0
	s_add_i32 m0, s55, 0x14000
	v_lshl_or_b32 v146, v5, 11, v2
	global_load_lds_dwordx4 v148, s[8:9]
	s_add_i32 m0, s55, 0x16000
	v_lshl_or_b32 v150, v4, 11, v2
	global_load_lds_dwordx4 v152, s[8:9]
	s_add_u32 s8, s88, s4
	s_addc_u32 s9, s89, s5
	s_add_i32 s60, s55, 0x2000
	s_mov_b32 m0, s55
	s_add_u32 s4, s8, 0x40000
	global_load_lds_dwordx4 v146, s[8:9]
	s_mov_b32 m0, s60
	s_addc_u32 s5, s9, 0
	s_add_i32 s61, s55, 0x4000
	global_load_lds_dwordx4 v150, s[8:9]
	s_mov_b32 m0, s61
	s_add_i32 s86, s55, 0x6000
	global_load_lds_dwordx4 v146, s[4:5]
	s_mov_b32 m0, s86
	v_mov_b32_e32 v155, 0
	global_load_lds_dwordx4 v150, s[4:5]
	v_mov_b32_e32 v149, v155
	v_mov_b32_e32 v153, v155
	v_mov_b32_e32 v147, v155
	v_mov_b32_e32 v151, v155
	s_cmp_eq_u32 s1, 1
	s_mov_b32 s87, 0
	v_lshl_add_u64 v[8:9], s[96:97], 0, v[148:149]
	v_lshl_add_u64 v[6:7], s[96:97], 0, v[152:153]
	v_lshl_add_u64 v[2:3], s[8:9], 0, v[146:147]
	s_cselect_b64 s[38:39], -1, 0
	s_cmp_lg_u32 s1, 1
	v_lshl_add_u64 v[4:5], s[8:9], 0, v[150:151]
	s_cbranch_scc1 .LBB0_1149
	s_setprio 1
	s_barrier

.LBB0_2639:
	s_andn2_b64 vcc, exec, s[0:1]
	s_cbranch_vccnz .LBB0_2711
	s_waitcnt lgkmcnt(0)
	v_lshrrev_b32_e32 v3, 1, v10
	v_lshrrev_b32_e32 v4, 5, v10
	v_and_b32_e32 v3, 24, v3
	v_and_b32_e32 v4, 4, v4
	v_bfe_u32 v5, v10, 2, 2
	v_lshlrev_b32_e32 v1, 4, v10
	v_and_b32_e32 v2, 32, v10
	v_bfe_u32 v13, v10, 2, 4
	v_or3_b32 v3, v4, v5, v3
	v_lshrrev_b32_e32 v4, 3, v10
	s_movk_i32 s1, 0x70
	v_bitop3_b32 v11, v1, v2, 48 bitop3:0x6c
	v_and_b32_e32 v12, 64, v10
	v_and_or_b32 v5, v4, s1, v13
	s_movk_i32 s1, 0x60
	v_add_u32_e32 v14, 0x2000, v1
	v_or_b32_e32 v2, v11, v12
	v_and_or_b32 v4, v4, s1, v3
	v_lshrrev_b32_e32 v1, 7, v14
	s_movk_i32 s1, 0xf0
	s_add_u32 s3, s28, 0x1700000
	v_lshl_or_b32 v132, v4, 11, v2
	v_and_or_b32 v4, v1, s1, v13
	s_movk_i32 s1, 0xe0
	s_addc_u32 s33, s29, 0
	v_and_or_b32 v1, v1, s1, v3
	s_lshr_b32 s1, s4, 6
	s_ashr_i32 s9, s8, 31
	s_ashr_i32 s7, s6, 31
	s_lshr_b32 s0, s4, 8
	s_lshl_b32 s35, s1, 10
	s_lshl_b64 s[12:13], s[8:9], 19
	s_lshl_b64 s[16:17], s[6:7], 19
	s_add_u32 s50, s3, s16
	s_addc_u32 s51, s33, s17
	s_add_i32 s54, s35, 0
	s_add_i32 m0, s54, 0x10000
	v_lshl_or_b32 v136, v1, 11, v2
	global_load_lds_dwordx4 v132, s[50:51]
	s_add_i32 m0, s54, 0x12000
	s_add_u32 s16, s50, 0x40000
	global_load_lds_dwordx4 v136, s[50:51]
	s_addc_u32 s17, s51, 0
	s_add_i32 m0, s54, 0x14000
	v_lshl_or_b32 v130, v5, 11, v2
	global_load_lds_dwordx4 v132, s[16:17]
	s_add_i32 m0, s54, 0x16000
	s_add_u32 s48, s88, s12
	s_addc_u32 s49, s89, s13
	s_add_i32 s55, s54, 0x2000
	global_load_lds_dwordx4 v136, s[16:17]
	s_mov_b32 m0, s54
	s_add_u32 s12, s48, 0x40000
	v_lshl_or_b32 v134, v4, 11, v2
	global_load_lds_dwordx4 v130, s[48:49]
	s_mov_b32 m0, s55
	s_addc_u32 s13, s49, 0
	s_add_i32 s56, s54, 0x4000
	global_load_lds_dwordx4 v134, s[48:49]
	s_mov_b32 m0, s56
	s_add_i32 s57, s54, 0x6000
	global_load_lds_dwordx4 v130, s[12:13]
	s_mov_b32 m0, s57
	v_mov_b32_e32 v139, 0
	global_load_lds_dwordx4 v134, s[12:13]
	v_mov_b32_e32 v133, v139
	v_mov_b32_e32 v137, v139
	v_mov_b32_e32 v131, v139
	v_mov_b32_e32 v135, v139
	s_cmp_eq_u32 s0, 1
	s_mov_b32 s58, 0
	v_lshl_add_u64 v[8:9], s[50:51], 0, v[132:133]
	v_lshl_add_u64 v[6:7], s[50:51], 0, v[136:137]
	v_lshl_add_u64 v[4:5], s[48:49], 0, v[130:131]
	v_lshl_add_u64 v[2:3], s[48:49], 0, v[134:135]
	s_cselect_b64 s[12:13], -1, 0
	s_cmp_lg_u32 s0, 1
	s_movk_i32 s59, 0x4000
	s_cbranch_scc1 .LBB0_2642
	s_setprio 1
	s_barrier

.LBB0_2858:
	v_lshrrev_b32_e32 v4, 1, v168
	v_and_b32_e32 v13, 24, v4
	v_lshrrev_b32_e32 v4, 5, v168
	s_ashr_i32 s0, s9, 3
	v_and_b32_e32 v4, 4, v4
	v_bfe_u32 v5, v168, 2, 2
	v_lshlrev_b32_e32 v2, 4, v168
	s_waitcnt lgkmcnt(0)
	v_and_b32_e32 v3, 32, v168
	v_bfe_u32 v12, v168, 2, 4
	v_or3_b32 v4, v4, v5, v13
	v_lshrrev_b32_e32 v5, 3, v168
	s_movk_i32 s9, 0x70
	s_add_i32 s0, s8, s0
	v_bitop3_b32 v10, v2, v3, 48 bitop3:0x6c
	v_and_b32_e32 v11, 64, v168
	v_and_or_b32 v6, v5, s9, v12
	s_movk_i32 s9, 0x60
	v_add_u32_e32 v14, 0x2000, v2
	s_ashr_i32 s8, s0, 31
	v_or_b32_e32 v3, v10, v11
	v_and_or_b32 v5, v5, s9, v4
	v_lshrrev_b32_e32 v2, 7, v14
	s_movk_i32 s9, 0xf0
	s_lshr_b32 s8, s8, 27
	v_lshl_or_b32 v144, v5, 11, v3
	v_and_or_b32 v5, v2, s9, v12
	s_movk_i32 s9, 0xe0
	s_add_i32 s8, s0, s8
	v_and_or_b32 v2, v2, s9, v4
	s_ashr_i32 s9, s8, 5
	s_andn2_b32 s8, s8, 31
	s_sub_i32 s8, s0, s8
	s_bfe_i32 s0, s8, 0x80000
	s_bfe_u32 s0, s0, 0x3000c
	s_add_i32 s11, s8, s0
	s_bfe_i32 s0, s11, 0x80000
	s_and_b32 s11, s11, 0xf8
	s_sub_i32 s8, s8, s11
	s_lshl_b32 s9, s9, 3
	s_sext_i32_i16 s0, s0
	s_sext_i32_i8 s8, s8
	s_lshr_b32 s1, s12, 8
	s_lshr_b32 s0, s0, 3
	s_add_i32 s40, s9, s8
	s_lshr_b32 s10, s12, 6
	s_ashr_i32 s41, s40, 31
	s_bfe_i64 s[16:17], s[0:1], 0x100000
	s_lshl_b32 s33, s10, 10
	s_lshl_b64 s[8:9], s[40:41], 19
	s_lshl_b64 s[16:17], s[16:17], 19
	s_add_u32 s44, s4, s16
	s_addc_u32 s45, s5, s17
	s_add_i32 s35, s33, 0
	s_add_i32 m0, s35, 0x10000
	v_lshl_or_b32 v148, v2, 11, v3
	global_load_lds_dwordx4 v144, s[44:45]
	s_add_i32 m0, s35, 0x12000
	s_add_u32 s16, s44, 0x40000
	global_load_lds_dwordx4 v148, s[44:45]
	s_addc_u32 s17, s45, 0
	s_add_i32 m0, s35, 0x14000
	v_lshl_or_b32 v142, v6, 11, v3
	global_load_lds_dwordx4 v144, s[16:17]
	s_add_i32 m0, s35, 0x16000
	s_add_u32 s42, s20, s8
	s_addc_u32 s43, s21, s9
	s_add_i32 s41, s35, 0x2000
	global_load_lds_dwordx4 v148, s[16:17]
	s_mov_b32 m0, s35
	s_add_u32 s8, s42, 0x40000
	v_lshl_or_b32 v146, v5, 11, v3
	global_load_lds_dwordx4 v142, s[42:43]
	s_mov_b32 m0, s41
	s_addc_u32 s9, s43, 0
	s_add_i32 s48, s35, 0x4000
	global_load_lds_dwordx4 v146, s[42:43]
	s_mov_b32 m0, s48
	s_add_i32 s49, s35, 0x6000
	global_load_lds_dwordx4 v142, s[8:9]
	s_mov_b32 m0, s49
	v_mov_b32_e32 v145, 0
	global_load_lds_dwordx4 v146, s[8:9]
	v_mov_b32_e32 v149, v145
	v_mov_b32_e32 v143, v145
	v_mov_b32_e32 v147, v145
	s_cmp_eq_u32 s1, 1
	s_mov_b32 s50, 0
	v_lshl_add_u64 v[8:9], s[44:45], 0, v[144:145]
	v_lshl_add_u64 v[6:7], s[44:45], 0, v[148:149]
	v_lshl_add_u64 v[2:3], s[42:43], 0, v[142:143]
	s_cselect_b64 s[8:9], -1, 0
	s_cmp_lg_u32 s1, 1
	v_lshl_add_u64 v[4:5], s[42:43], 0, v[146:147]
	s_cbranch_scc1 .LBB0_2860
	s_setprio 1
	s_barrier

.LBB0_2904:
	v_lshrrev_b32_e32 v4, 1, v161
	v_lshrrev_b32_e32 v5, 5, v161
	s_ashr_i32 s0, s5, 3
	v_and_b32_e32 v4, 24, v4
	v_and_b32_e32 v5, 4, v5
	v_bfe_u32 v6, v161, 2, 2
	v_lshlrev_b32_e32 v2, 4, v161
	s_waitcnt lgkmcnt(0)
	v_and_b32_e32 v3, 32, v161
	v_bfe_u32 v12, v161, 2, 4
	v_or3_b32 v4, v5, v6, v4
	v_lshrrev_b32_e32 v5, 3, v161
	s_movk_i32 s5, 0x70
	s_add_i32 s0, s4, s0
	v_bitop3_b32 v10, v2, v3, 48 bitop3:0x6c
	v_and_b32_e32 v11, 64, v161
	v_and_or_b32 v6, v5, s5, v12
	s_movk_i32 s5, 0x60
	v_add_u32_e32 v13, 0x2000, v2
	s_ashr_i32 s4, s0, 31
	v_or_b32_e32 v3, v10, v11
	v_and_or_b32 v5, v5, s5, v4
	v_lshrrev_b32_e32 v2, 7, v13
	s_movk_i32 s5, 0xf0
	s_lshr_b32 s4, s4, 26
	v_lshl_or_b32 v132, v5, 11, v3
	v_and_or_b32 v5, v2, s5, v12
	s_movk_i32 s5, 0xe0
	s_add_i32 s4, s0, s4
	v_and_or_b32 v2, v2, s5, v4
	s_ashr_i32 s5, s4, 6
	s_andn2_b32 s4, s4, 63
	s_sub_i32 s4, s0, s4
	s_bfe_i32 s0, s4, 0x80000
	s_bfe_u32 s0, s0, 0x3000c
	s_add_i32 s8, s4, s0
	s_bfe_i32 s0, s8, 0x80000
	s_and_b32 s8, s8, 0xf8
	s_sub_i32 s4, s4, s8
	s_lshl_b32 s5, s5, 3
	s_sext_i32_i16 s0, s0
	s_sext_i32_i8 s4, s4
	s_lshr_b32 s1, s16, 8
	s_lshr_b32 s0, s0, 3
	s_add_i32 s4, s5, s4
	s_lshr_b32 s10, s16, 6
	s_ashr_i32 s5, s4, 31
	s_bfe_i64 s[18:19], s[0:1], 0x100000
	s_lshl_b32 s21, s10, 10
	s_lshl_b64 s[8:9], s[4:5], 19
	s_lshl_b64 s[18:19], s[18:19], 19
	s_add_u32 s46, s6, s18
	s_addc_u32 s47, s7, s19
	s_add_i32 s33, s21, 0
	s_add_i32 m0, s33, 0x10000
	v_lshl_or_b32 v136, v2, 11, v3
	global_load_lds_dwordx4 v132, s[46:47]
	s_add_i32 m0, s33, 0x12000
	s_add_u32 s18, s46, 0x40000
	global_load_lds_dwordx4 v136, s[46:47]
	s_addc_u32 s19, s47, 0
	s_add_i32 m0, s33, 0x14000
	v_lshl_or_b32 v130, v6, 11, v3
	global_load_lds_dwordx4 v132, s[18:19]
	s_add_i32 m0, s33, 0x16000
	s_add_u32 s44, s88, s8
	s_addc_u32 s45, s89, s9
	s_add_i32 s35, s33, 0x2000
	global_load_lds_dwordx4 v136, s[18:19]
	s_mov_b32 m0, s33
	s_add_u32 s8, s44, 0x40000
	v_lshl_or_b32 v134, v5, 11, v3
	global_load_lds_dwordx4 v130, s[44:45]
	s_mov_b32 m0, s35
	s_addc_u32 s9, s45, 0
	s_add_i32 s50, s33, 0x4000
	global_load_lds_dwordx4 v134, s[44:45]
	s_mov_b32 m0, s50
	s_add_i32 s51, s33, 0x6000
	global_load_lds_dwordx4 v130, s[8:9]
	s_mov_b32 m0, s51
	v_mov_b32_e32 v133, 0
	global_load_lds_dwordx4 v134, s[8:9]
	v_mov_b32_e32 v137, v133
	v_mov_b32_e32 v131, v133
	v_mov_b32_e32 v135, v133
	s_cmp_eq_u32 s1, 1
	s_mov_b32 s52, 0
	v_lshl_add_u64 v[8:9], s[46:47], 0, v[132:133]
	v_lshl_add_u64 v[6:7], s[46:47], 0, v[136:137]
	v_lshl_add_u64 v[2:3], s[44:45], 0, v[130:131]
	s_cselect_b64 s[8:9], -1, 0
	s_cmp_lg_u32 s1, 1
	v_lshl_add_u64 v[4:5], s[44:45], 0, v[134:135]
	s_cbranch_scc1 .LBB0_2906
	s_setprio 1
	s_barrier

.LBB0_2922:
	s_waitcnt vmcnt(0)
	s_setprio 0
	v_readlane_b32 s76, v238, 53
	v_readlane_b32 s77, v238, 54
	s_barrier

.LBB0_3017:
	v_lshrrev_b32_e32 v4, 1, v164
	v_and_b32_e32 v13, 24, v4
	v_lshrrev_b32_e32 v4, 5, v164
	s_ashr_i32 s0, s11, 3
	v_and_b32_e32 v4, 4, v4
	v_bfe_u32 v5, v164, 2, 2
	v_lshlrev_b32_e32 v2, 4, v164
	s_waitcnt lgkmcnt(0)
	v_and_b32_e32 v3, 32, v164
	v_bfe_u32 v12, v164, 2, 4
	v_or3_b32 v4, v4, v5, v13
	v_lshrrev_b32_e32 v5, 3, v164
	s_movk_i32 s11, 0x70
	s_add_i32 s0, s10, s0
	v_bitop3_b32 v10, v2, v3, 48 bitop3:0x6c
	v_and_b32_e32 v11, 64, v164
	v_and_or_b32 v6, v5, s11, v12
	s_movk_i32 s11, 0x60
	v_add_u32_e32 v14, 0x2000, v2
	s_ashr_i32 s10, s0, 31
	v_or_b32_e32 v3, v10, v11
	v_and_or_b32 v5, v5, s11, v4
	v_lshrrev_b32_e32 v2, 7, v14
	s_movk_i32 s11, 0xf0
	s_lshr_b32 s10, s10, 27
	v_lshl_or_b32 v140, v5, 11, v3
	v_and_or_b32 v5, v2, s11, v12
	s_movk_i32 s11, 0xe0
	s_add_i32 s10, s0, s10
	v_and_or_b32 v2, v2, s11, v4
	s_ashr_i32 s11, s10, 5
	s_andn2_b32 s10, s10, 31
	s_sub_i32 s10, s0, s10
	s_bfe_i32 s0, s10, 0x80000
	s_bfe_u32 s0, s0, 0x3000c
	s_add_i32 s13, s10, s0
	s_bfe_i32 s0, s13, 0x80000
	s_and_b32 s13, s13, 0xf8
	s_sub_i32 s10, s10, s13
	s_lshl_b32 s11, s11, 3
	s_sext_i32_i16 s0, s0
	s_sext_i32_i8 s10, s10
	s_lshr_b32 s1, s16, 8
	s_lshr_b32 s0, s0, 3
	s_add_i32 s38, s11, s10
	s_lshr_b32 s12, s16, 6
	s_ashr_i32 s39, s38, 31
	s_bfe_i64 s[18:19], s[0:1], 0x100000
	s_lshl_b32 s33, s12, 10
	s_lshl_b64 s[10:11], s[38:39], 19
	s_lshl_b64 s[18:19], s[18:19], 19
	s_add_u32 s42, s4, s18
	s_addc_u32 s43, s5, s19
	s_add_i32 s35, s33, 0
	s_add_i32 m0, s35, 0x10000
	v_lshl_or_b32 v144, v2, 11, v3
	global_load_lds_dwordx4 v140, s[42:43]
	s_add_i32 m0, s35, 0x12000
	s_add_u32 s18, s42, 0x40000
	global_load_lds_dwordx4 v144, s[42:43]
	s_addc_u32 s19, s43, 0
	s_add_i32 m0, s35, 0x14000
	v_lshl_or_b32 v138, v6, 11, v3
	global_load_lds_dwordx4 v140, s[18:19]
	s_add_i32 m0, s35, 0x16000
	s_add_u32 s40, s14, s10
	s_addc_u32 s41, s15, s11
	s_add_i32 s39, s35, 0x2000
	global_load_lds_dwordx4 v144, s[18:19]
	s_mov_b32 m0, s35
	s_add_u32 s10, s40, 0x40000
	v_lshl_or_b32 v142, v5, 11, v3
	global_load_lds_dwordx4 v138, s[40:41]
	s_mov_b32 m0, s39
	s_addc_u32 s11, s41, 0
	s_add_i32 s46, s35, 0x4000
	global_load_lds_dwordx4 v142, s[40:41]
	s_mov_b32 m0, s46
	s_add_i32 s47, s35, 0x6000
	global_load_lds_dwordx4 v138, s[10:11]
	s_mov_b32 m0, s47
	v_mov_b32_e32 v141, 0
	global_load_lds_dwordx4 v142, s[10:11]
	v_mov_b32_e32 v145, v141
	v_mov_b32_e32 v139, v141
	v_mov_b32_e32 v143, v141
	s_cmp_eq_u32 s1, 1
	s_mov_b32 s48, 0
	v_lshl_add_u64 v[8:9], s[42:43], 0, v[140:141]
	v_lshl_add_u64 v[6:7], s[42:43], 0, v[144:145]
	v_lshl_add_u64 v[2:3], s[40:41], 0, v[138:139]
	s_cselect_b64 s[10:11], -1, 0
	s_cmp_lg_u32 s1, 1
	v_lshl_add_u64 v[4:5], s[40:41], 0, v[142:143]
	s_cbranch_scc1 .LBB0_3019
	s_setprio 1
	s_barrier

.LBB0_3118:
	s_add_u32 s8, s28, 0x2700000
	v_bfe_u32 v165, v1, 4, 2
	v_cndmask_b32_e64 v2, 0, 1, s[4:5]
	s_addc_u32 s9, s29, 0
	v_lshlrev_b32_e32 v162, 4, v1
	v_and_b32_e32 v164, 15, v1
	v_cmp_ne_u32_e64 s[0:1], 1, v2
	s_andn2_b64 vcc, exec, s[4:5]
	v_lshlrev_b32_e32 v163, 3, v165
	s_cbranch_vccnz .LBB0_3186
	s_waitcnt lgkmcnt(0)
	v_lshrrev_b32_e32 v3, 1, v1
	v_lshrrev_b32_e32 v4, 5, v1
	v_and_b32_e32 v3, 24, v3
	v_and_b32_e32 v4, 4, v4
	v_bfe_u32 v5, v1, 2, 2
	v_and_b32_e32 v2, 32, v1
	v_bfe_u32 v12, v1, 2, 4
	v_or3_b32 v3, v4, v5, v3
	v_lshrrev_b32_e32 v4, 3, v1
	s_movk_i32 s3, 0x70
	v_bitop3_b32 v10, v162, v2, 48 bitop3:0x6c
	v_and_b32_e32 v11, 64, v1
	v_and_or_b32 v5, v4, s3, v12
	s_movk_i32 s3, 0x60
	v_or_b32_e32 v2, v10, v11
	v_and_or_b32 v4, v4, s3, v3
	v_add_u32_e32 v13, 0x2000, v162
	v_lshl_or_b32 v142, v4, 11, v2
	v_lshrrev_b32_e32 v4, 7, v13
	s_movk_i32 s3, 0xf0
	s_lshr_b32 s4, s6, 6
	v_lshl_or_b32 v140, v5, 11, v2
	v_and_or_b32 v5, v4, s3, v12
	s_movk_i32 s3, 0xe0
	s_ashr_i32 s43, s42, 31
	s_ashr_i32 s11, s10, 31
	v_and_or_b32 v3, v4, s3, v3
	s_lshr_b32 s5, s6, 8
	s_lshl_b32 s3, s4, 10
	s_lshl_b64 s[16:17], s[42:43], 19
	s_lshl_b64 s[18:19], s[10:11], 19
	s_add_u32 s46, s8, s18
	s_addc_u32 s47, s9, s19
	s_add_i32 s33, s3, 0
	s_add_i32 m0, s33, 0x10000
	v_lshl_or_b32 v146, v3, 11, v2
	global_load_lds_dwordx4 v142, s[46:47]
	s_add_i32 m0, s33, 0x12000
	s_add_u32 s18, s46, 0x40000
	global_load_lds_dwordx4 v146, s[46:47]
	s_addc_u32 s19, s47, 0
	s_add_i32 m0, s33, 0x14000
	v_lshl_or_b32 v144, v5, 11, v2
	global_load_lds_dwordx4 v142, s[18:19]
	s_add_i32 m0, s33, 0x16000
	s_add_u32 s44, s62, s16
	s_addc_u32 s45, s63, s17
	s_add_i32 s35, s33, 0x2000
	global_load_lds_dwordx4 v146, s[18:19]
	s_mov_b32 m0, s33
	s_add_u32 s16, s44, 0x40000
	global_load_lds_dwordx4 v140, s[44:45]
	s_mov_b32 m0, s35
	s_addc_u32 s17, s45, 0
	s_add_i32 s50, s33, 0x4000
	global_load_lds_dwordx4 v144, s[44:45]
	s_mov_b32 m0, s50
	s_add_i32 s51, s33, 0x6000
	global_load_lds_dwordx4 v140, s[16:17]
	s_mov_b32 m0, s51
	v_mov_b32_e32 v143, 0
	global_load_lds_dwordx4 v144, s[16:17]
	v_mov_b32_e32 v147, v143
	v_mov_b32_e32 v141, v143
	v_mov_b32_e32 v145, v143
	s_cmp_eq_u32 s5, 1
	s_mov_b32 s11, 0
	v_lshl_add_u64 v[8:9], s[46:47], 0, v[142:143]
	v_lshl_add_u64 v[6:7], s[46:47], 0, v[146:147]
	v_lshl_add_u64 v[2:3], s[44:45], 0, v[140:141]
	s_cselect_b64 s[16:17], -1, 0
	s_cmp_lg_u32 s5, 1
	v_lshl_add_u64 v[4:5], s[44:45], 0, v[144:145]
	s_cbranch_scc1 .LBB0_3121
	s_setprio 1
	s_barrier

.LBB0_3281:
	s_waitcnt lgkmcnt(0)
	v_lshrrev_b32_e32 v3, 1, v10
	v_lshrrev_b32_e32 v4, 5, v10
	v_and_b32_e32 v3, 24, v3
	v_and_b32_e32 v4, 4, v4
	v_bfe_u32 v5, v10, 2, 2
	s_ashr_i32 s0, s5, 3
	v_lshlrev_b32_e32 v1, 4, v10
	v_and_b32_e32 v2, 32, v10
	v_bfe_u32 v13, v10, 2, 4
	v_or3_b32 v3, v4, v5, v3
	v_lshrrev_b32_e32 v4, 3, v10
	s_movk_i32 s5, 0x70
	s_add_u32 s33, s28, 0x2900000
	v_bitop3_b32 v11, v1, v2, 48 bitop3:0x6c
	v_and_b32_e32 v12, 64, v10
	v_and_or_b32 v5, v4, s5, v13
	s_movk_i32 s5, 0x60
	v_add_u32_e32 v14, 0x2000, v1
	s_addc_u32 s35, s29, 0
	v_or_b32_e32 v2, v11, v12
	v_and_or_b32 v4, v4, s5, v3
	v_lshrrev_b32_e32 v1, 7, v14
	s_movk_i32 s5, 0xf0
	s_add_i32 s0, s4, s0
	v_lshl_or_b32 v132, v4, 11, v2
	v_and_or_b32 v4, v1, s5, v13
	s_movk_i32 s5, 0xe0
	s_mul_hi_i32 s4, s0, 0x2e8ba2e9
	v_and_or_b32 v1, v1, s5, v3
	s_lshr_b32 s5, s4, 31
	s_ashr_i32 s4, s4, 5
	s_add_i32 s4, s4, s5
	s_lshl_b32 s8, s4, 3
	s_sub_i32 s5, 0x45, s8
	s_mulk_i32 s4, 0xb0
	s_min_u32 s9, s5, 8
	s_sub_i32 s11, s0, s4
	v_lshl_or_b32 v130, v5, 11, v2
	v_lshl_or_b32 v134, v4, 11, v2
	v_lshl_or_b32 v136, v1, 11, v2
	s_sext_i32_i16 s0, s11
	v_cvt_f32_ubyte0_e32 v2, s9
	v_cvt_f32_i32_e32 v1, s0
	v_rcp_iflag_f32_e32 v3, v2
	s_lshr_b32 s10, s14, 6
	s_ashr_i32 s0, s0, 30
	s_lshr_b32 s1, s14, 8
	v_mul_f32_e32 v3, v1, v3
	v_trunc_f32_e32 v3, v3
	v_fma_f32 v1, -v3, v2, v1
	v_cvt_i32_f32_e32 v3, v3
	s_lshl_b32 s40, s10, 10
	s_or_b32 s0, s0, 1
	v_cmp_ge_f32_e64 s[4:5], |v1|, v2
	s_and_b64 s[4:5], s[4:5], exec
	s_cselect_b32 s0, s0, 0
	v_readfirstlane_b32 s4, v3
	s_add_i32 s0, s4, s0
	s_mul_i32 s4, s0, s9
	s_sub_i32 s4, s11, s4
	s_sext_i32_i16 s4, s4
	s_add_i32 s4, s8, s4
	s_ashr_i32 s5, s4, 31
	s_bfe_i64 s[16:17], s[0:1], 0x100000
	s_lshl_b64 s[8:9], s[4:5], 19
	s_lshl_b64 s[16:17], s[16:17], 19
	s_add_u32 s36, s33, s16
	s_addc_u32 s37, s35, s17
	s_add_i32 s41, s40, 0
	s_add_i32 m0, s41, 0x10000
	v_mov_b32_e32 v133, 0
	global_load_lds_dwordx4 v132, s[36:37]
	s_add_i32 m0, s41, 0x12000
	s_add_u32 s16, s36, 0x40000
	global_load_lds_dwordx4 v136, s[36:37]
	s_addc_u32 s17, s37, 0
	s_add_i32 m0, s41, 0x14000
	v_mov_b32_e32 v137, v133
	global_load_lds_dwordx4 v132, s[16:17]
	s_add_i32 m0, s41, 0x16000
	s_add_u32 s22, s88, s8
	s_addc_u32 s23, s89, s9
	s_add_i32 s42, s41, 0x2000
	global_load_lds_dwordx4 v136, s[16:17]
	s_mov_b32 m0, s41
	s_add_u32 s8, s22, 0x40000
	global_load_lds_dwordx4 v130, s[22:23]
	s_mov_b32 m0, s42
	s_addc_u32 s9, s23, 0
	s_add_i32 s43, s41, 0x4000
	global_load_lds_dwordx4 v134, s[22:23]
	s_mov_b32 m0, s43
	s_add_i32 s44, s41, 0x6000
	global_load_lds_dwordx4 v130, s[8:9]
	s_mov_b32 m0, s44
	v_mov_b32_e32 v131, v133
	global_load_lds_dwordx4 v134, s[8:9]
	v_mov_b32_e32 v135, v133
	s_cmp_eq_u32 s1, 1
	s_mov_b32 s45, 0
	v_lshl_add_u64 v[8:9], s[36:37], 0, v[132:133]
	v_lshl_add_u64 v[6:7], s[36:37], 0, v[136:137]
	v_lshl_add_u64 v[2:3], s[22:23], 0, v[130:131]
	s_cselect_b64 s[8:9], -1, 0
	s_cmp_lg_u32 s1, 1
	v_lshl_add_u64 v[4:5], s[22:23], 0, v[134:135]
	s_cbranch_scc1 .LBB0_3283
	s_setprio 1
	s_barrier

.LBB0_3362:
	s_andn2_b64 vcc, exec, s[0:1]
	s_cbranch_vccnz .LBB0_3434
	v_lshrrev_b32_e32 v4, 1, v140
	v_lshrrev_b32_e32 v5, 5, v140
	v_and_b32_e32 v4, 24, v4
	v_and_b32_e32 v5, 4, v5
	v_bfe_u32 v6, v140, 2, 2
	v_lshlrev_b32_e32 v1, 4, v140
	v_and_b32_e32 v2, 32, v140
	s_waitcnt lgkmcnt(0)
	v_bfe_u32 v3, v140, 2, 4
	v_or3_b32 v4, v5, v6, v4
	v_lshrrev_b32_e32 v5, 3, v140
	s_movk_i32 s1, 0x70
	v_bitop3_b32 v10, v1, v2, 48 bitop3:0x6c
	v_and_or_b32 v6, v5, s1, v3
	s_movk_i32 s1, 0x60
	v_add_u32_e32 v1, 0x2000, v1
	v_and_or_b32 v5, v5, s1, v4
	v_lshrrev_b32_e32 v1, 7, v1
	s_movk_i32 s1, 0xf0
	s_lshr_b32 s0, s6, 6
	v_and_b32_e32 v11, 64, v140
	v_and_or_b32 v3, v1, s1, v3
	s_movk_i32 s1, 0xe0
	v_or_b32_e32 v2, v10, v11
	v_and_or_b32 v1, v1, s1, v4
	s_lshr_b32 s1, s6, 8
	s_lshl_b32 s3, s0, 10
	s_mul_i32 s5, s10, 0x160000
	v_lshrrev_b32_e32 v2, 1, v2
	v_mul_u32_u24_e32 v5, 0xb00, v5
	s_mul_hi_i32 s4, s10, 0x160000
	s_add_u32 s40, s12, s5
	v_or_b32_e32 v5, v5, v2
	s_addc_u32 s41, s13, s4
	s_add_i32 s33, s3, 0
	v_lshlrev_b32_e32 v144, 1, v5
	v_mul_u32_u24_e32 v1, 0xb00, v1
	s_add_i32 m0, s33, 0x10000
	v_or_b32_e32 v1, v1, v2
	global_load_lds_dwordx4 v144, s[40:41]
	s_add_i32 m0, s33, 0x12000
	v_lshlrev_b32_e32 v148, 1, v1
	s_add_u32 s4, s40, 0xb0000
	global_load_lds_dwordx4 v148, s[40:41]
	s_addc_u32 s5, s41, 0
	s_add_i32 m0, s33, 0x14000
	s_mul_i32 s11, s60, 0x160000
	global_load_lds_dwordx4 v144, s[4:5]
	s_add_i32 m0, s33, 0x16000
	v_mul_u32_u24_e32 v12, 0xb00, v6
	s_mul_hi_i32 s7, s60, 0x160000
	s_add_u32 s38, s64, s11
	v_or_b32_e32 v6, v2, v12
	v_mul_u32_u24_e32 v13, 0xb00, v3
	s_addc_u32 s39, s65, s7
	s_add_i32 s35, s33, 0x2000
	v_lshlrev_b32_e32 v142, 1, v6
	v_or_b32_e32 v3, v13, v2
	global_load_lds_dwordx4 v148, s[4:5]
	s_mov_b32 m0, s33
	s_add_u32 s4, s38, 0xb0000
	v_lshlrev_b32_e32 v146, 1, v3
	global_load_lds_dwordx4 v142, s[38:39]
	s_mov_b32 m0, s35
	s_addc_u32 s5, s39, 0
	s_add_i32 s44, s33, 0x4000
	global_load_lds_dwordx4 v146, s[38:39]
	s_mov_b32 m0, s44
	s_add_i32 s45, s33, 0x6000
	global_load_lds_dwordx4 v142, s[4:5]
	s_mov_b32 m0, s45
	v_mov_b32_e32 v145, 0
	global_load_lds_dwordx4 v146, s[4:5]
	v_mov_b32_e32 v149, v145
	v_mov_b32_e32 v143, v145
	v_mov_b32_e32 v147, v145
	s_cmp_eq_u32 s1, 1
	s_mov_b32 s11, 0
	v_lshl_add_u64 v[8:9], s[40:41], 0, v[144:145]
	v_lshl_add_u64 v[6:7], s[40:41], 0, v[148:149]
	v_lshl_add_u64 v[2:3], s[38:39], 0, v[142:143]
	s_cselect_b64 s[14:15], -1, 0
	s_cmp_lg_u32 s1, 1
	v_lshl_add_u64 v[4:5], s[38:39], 0, v[146:147]
	s_cbranch_scc1 .LBB0_3365
	s_setprio 1
	s_barrier

.LBB0_3441:
	s_ashr_i32 s6, s6, 3
	s_add_i32 s5, s5, s6
	s_ashr_i32 s6, s5, 31
	s_lshr_b32 s6, s6, 27
	s_waitcnt lgkmcnt(0)
	v_lshrrev_b32_e32 v3, 1, v140
	v_lshrrev_b32_e32 v4, 5, v140
	s_add_i32 s6, s5, s6
	v_and_b32_e32 v3, 24, v3
	v_and_b32_e32 v4, 4, v4
	v_bfe_u32 v5, v140, 2, 2
	s_ashr_i32 s7, s6, 5
	s_andn2_b32 s6, s6, 31
	v_lshlrev_b32_e32 v152, 4, v140
	v_and_b32_e32 v1, 32, v140
	v_bfe_u32 v2, v140, 2, 4
	v_or3_b32 v3, v4, v5, v3
	v_lshrrev_b32_e32 v4, 3, v140
	s_movk_i32 s0, 0x70
	s_sub_i32 s6, s5, s6
	v_bitop3_b32 v10, v152, v1, 48 bitop3:0x6c
	v_and_b32_e32 v11, 64, v140
	v_and_or_b32 v5, v4, s0, v2
	s_movk_i32 s0, 0x60
	s_bfe_i32 s5, s6, 0x80000
	v_or_b32_e32 v1, v10, v11
	v_and_or_b32 v4, v4, s0, v3
	s_bfe_u32 s5, s5, 0x3000c
	v_lshrrev_b32_e32 v1, 1, v1
	v_mul_u32_u24_e32 v4, 0xb00, v4
	s_add_i32 s10, s6, s5
	v_or_b32_e32 v4, v4, v1
	s_bfe_i32 s5, s10, 0x80000
	s_and_b32 s10, s10, 0xf8
	v_lshlrev_b32_e32 v132, 1, v4
	v_add_u32_e32 v4, 0x2000, v152
	s_sub_i32 s6, s6, s10
	v_lshrrev_b32_e32 v4, 7, v4
	s_movk_i32 s0, 0xf0
	s_lshl_b32 s7, s7, 3
	s_sext_i32_i16 s11, s5
	s_sext_i32_i8 s6, s6
	s_lshr_b32 s1, s4, 6
	v_and_or_b32 v2, v4, s0, v2
	s_movk_i32 s0, 0xe0
	s_add_i32 s10, s7, s6
	s_ashr_i32 s6, s11, 3
	v_and_or_b32 v3, v4, s0, v3
	s_lshr_b32 s0, s4, 8
	s_lshl_b32 s33, s1, 10
	s_lshr_b32 s5, s11, 3
	s_mul_hi_i32 s7, s6, 0x160000
	s_mul_i32 s6, s6, 0x160000
	v_mul_u32_u24_e32 v13, 0xb00, v2
	s_add_u32 s42, s12, s6
	v_or_b32_e32 v2, v13, v1
	s_addc_u32 s43, s13, s7
	s_add_i32 s35, s33, 0
	v_mul_u32_u24_e32 v12, 0xb00, v5
	v_lshlrev_b32_e32 v134, 1, v2
	v_mul_u32_u24_e32 v2, 0xb00, v3
	s_add_i32 m0, s35, 0x10000
	v_or_b32_e32 v5, v1, v12
	v_or_b32_e32 v1, v2, v1
	global_load_lds_dwordx4 v132, s[42:43]
	s_add_i32 m0, s35, 0x12000
	v_lshlrev_b32_e32 v136, 1, v1
	s_add_u32 s6, s42, 0xb0000
	global_load_lds_dwordx4 v136, s[42:43]
	s_addc_u32 s7, s43, 0
	s_add_i32 m0, s35, 0x14000
	s_mul_i32 s15, s10, 0x160000
	global_load_lds_dwordx4 v132, s[6:7]
	s_add_i32 m0, s35, 0x16000
	s_mul_hi_i32 s14, s10, 0x160000
	s_add_u32 s40, s64, s15
	s_addc_u32 s41, s65, s14
	s_add_i32 s48, s35, 0x2000
	v_lshlrev_b32_e32 v130, 1, v5
	global_load_lds_dwordx4 v136, s[6:7]
	s_mov_b32 m0, s35
	s_add_u32 s6, s40, 0xb0000
	global_load_lds_dwordx4 v130, s[40:41]
	s_mov_b32 m0, s48
	s_addc_u32 s7, s41, 0
	s_add_i32 s49, s35, 0x4000
	global_load_lds_dwordx4 v134, s[40:41]
	s_mov_b32 m0, s49
	s_add_i32 s50, s35, 0x6000
	global_load_lds_dwordx4 v130, s[6:7]
	s_mov_b32 m0, s50
	v_mov_b32_e32 v133, 0
	global_load_lds_dwordx4 v134, s[6:7]
	v_mov_b32_e32 v137, v133
	v_mov_b32_e32 v131, v133
	v_mov_b32_e32 v135, v133
	s_cmp_eq_u32 s0, 1
	v_lshl_add_u64 v[8:9], s[42:43], 0, v[132:133]
	v_lshl_add_u64 v[6:7], s[42:43], 0, v[136:137]
	v_lshl_add_u64 v[2:3], s[40:41], 0, v[130:131]
	s_cselect_b64 s[14:15], -1, 0
	s_cmp_lg_u32 s0, 1
	v_lshl_add_u64 v[4:5], s[40:41], 0, v[134:135]
	s_cbranch_scc1 .LBB0_3443
	s_setprio 1
	s_barrier

.LBB0_3464:
	v_lshlrev_b32_e32 v130, 3, v153
	s_lshl_b32 s3, s10, 8
	s_lshl_b32 s4, s53, 8
	v_lshl_or_b32 v130, s11, 5, v130
	v_or_b32_e32 v132, s4, v130
	v_add_u32_e32 v130, s3, v1
	v_ashrrev_i32_e32 v131, 31, v130
	v_lshlrev_b64 v[130:131], 12, v[130:131]
	v_lshl_add_u64 v[130:131], s[26:27], 0, v[130:131]
	v_ashrrev_i32_e32 v133, 31, v132
	v_lshl_add_u64 v[130:131], v[132:133], 2, v[130:131]
	s_waitcnt vmcnt(0)
	s_setprio 0
	s_barrier
	global_load_dwordx4 v[134:137], v[130:131], off
	global_load_dwordx4 v[142:145], v[130:131], off offset:16
	global_load_dwordx4 v[146:149], v[130:131], off offset:512
	global_load_dwordx4 v[154:157], v[130:131], off offset:528
	v_mbcnt_lo_u32_b32 v138, -1, 0
	v_mbcnt_hi_u32_b32 v138, -1, v138
	v_and_b32_e32 v150, 64, v138
	v_xor_b32_e32 v139, 16, v138
	v_add_u32_e32 v151, 64, v150
	v_cmp_lt_i32_e32 vcc, v139, v151
	s_lshl_b32 s0, s11, 2
	s_add_i32 s5, s0, 0
	v_cndmask_b32_e32 v139, v138, v139, vcc
	v_lshlrev_b32_e32 v150, 2, v139
	s_waitcnt vmcnt(0)
	v_pk_fma_f32 v[128:129], v[128:129], 0.5, v[136:137] op_sel_hi:[1,0,1]
	v_pk_fma_f32 v[134:135], v[126:127], 0.5, v[134:135] op_sel_hi:[1,0,1]
	v_pk_fma_f32 v[124:125], v[124:125], 0.5, v[144:145] op_sel_hi:[1,0,1]
	v_pk_fma_f32 v[126:127], v[122:123], 0.5, v[142:143] op_sel_hi:[1,0,1]
	v_pk_fma_f32 v[120:121], v[120:121], 0.5, v[148:149] op_sel_hi:[1,0,1]
	v_pk_fma_f32 v[122:123], v[118:119], 0.5, v[146:147] op_sel_hi:[1,0,1]
	v_pk_fma_f32 v[116:117], v[116:117], 0.5, v[156:157] op_sel_hi:[1,0,1]
	v_pk_fma_f32 v[118:119], v[114:115], 0.5, v[154:155] op_sel_hi:[1,0,1]
	v_mul_f32_e32 v114, v135, v135
	v_mul_f32_e32 v115, v129, v129
	v_mul_f32_e32 v136, v127, v127
	v_mul_f32_e32 v137, v125, v125
	v_mul_f32_e32 v139, v123, v123
	v_mul_f32_e32 v142, v121, v121
	v_mul_f32_e32 v143, v119, v119
	v_mul_f32_e32 v144, v117, v117
	v_fmac_f32_e32 v114, v134, v134
	v_fmac_f32_e32 v115, v128, v128
	v_fmac_f32_e32 v136, v126, v126
	v_fmac_f32_e32 v137, v124, v124
	v_fmac_f32_e32 v139, v122, v122
	v_fmac_f32_e32 v142, v120, v120
	v_fmac_f32_e32 v143, v118, v118
	v_fmac_f32_e32 v144, v116, v116
	v_add_f32_e32 v114, v114, v115
	v_add_f32_e32 v115, v136, v137
	v_add_f32_e32 v136, v139, v142
	v_add_f32_e32 v137, v143, v144
	v_add_f32_e32 v114, v114, v115
	v_add_f32_e32 v115, v136, v137
	v_add_f32_e32 v114, v114, v115
	ds_bpermute_b32 v115, v150, v114
	v_xor_b32_e32 v136, 32, v138
	v_cmp_lt_i32_e32 vcc, v136, v151
	s_waitcnt lgkmcnt(0)
	v_add_f32_e32 v114, v114, v115
	v_cndmask_b32_e32 v136, v138, v136, vcc
	v_lshlrev_b32_e32 v151, 2, v136
	ds_bpermute_b32 v115, v151, v114
	v_cmp_eq_u32_e32 vcc, 0, v153
	s_and_saveexec_b64 s[0:1], vcc
	s_cbranch_execz .LBB0_3466
	v_lshl_add_u32 v136, v1, 4, s5
	s_waitcnt lgkmcnt(0)
	v_add_f32_e32 v114, v114, v115
	ds_write_b32 v136, v114
